# speedup vs baseline: 1.0086x; 1.0019x over previous
; #define PG8_STAGE(bufoff, gbase, voff) do { _Pragma("unroll") for (int _i = 0; _i < 2; ++_i) \
;         __builtin_amdgcn_global_load_lds((const unsigned*)((const char*)(gbase) + (voff)[_i]), (LAS unsigned*)(lds + (bufoff) + ldsw + _i * 8192), 16, 0, 0); } while (0)
; #define PG8_LDA(dst, b, h) do { _Pragma("unroll") for (int m = 0; m < 4; ++m) _Pragma("unroll") for (int k = 0; k < 2; ++k) dst[m][k] = *(const LAS bf16x8*)(lds + PG8_SA(b, h) + aoff + m * 2048 + k * 1024); } while (0)
; #define PG8_LDB(dst, b, h) do { _Pragma("unroll") for (int n = 0; n < 2; ++n) _Pragma("unroll") for (int k = 0; k < 2; ++k) dst[n][k] = *(const LAS bf16x8*)(lds + PG8_SB(b, h) + boff + n * 2048 + k * 1024); } while (0)
; #define PG8_MMA(ai, bj, At, Bt) do { __builtin_amdgcn_s_setprio(1); _Pragma("unroll") for (int m = 0; m < 4; ++m) _Pragma("unroll") for (int n = 0; n < 2; ++n) _Pragma("unroll") for (int k = 0; k < 2; ++k) \
;         acc[ai][bj][m][n] = __builtin_amdgcn_mfma_f32_16x16x32_bf16(Bt[n][k], At[m][k], acc[ai][bj][m][n], 0, 0, 0); __builtin_amdgcn_s_setprio(0); } while (0)
; #define PG8_WAIT_L(n) asm volatile("s_waitcnt lgkmcnt(" #n ")" ::: "memory")
; #define PG8_BAR __builtin_amdgcn_s_barrier()
; #define PG8_SCHED __builtin_amdgcn_sched_barrier(0)
; __device__ __forceinline__ void gemm_phase(LAS unsigned char* lds, const GemmD& g) {
;     ...
;         for (int t = 0; t < nt; t += 2) {
;             const bool last = (t == nt - 2);
;             const char* a1 = cA + (size_t)(t + 1) * kstep;
;             const char* a2 = last ? nA : cA + (size_t)(t + 2) * kstep; const char* b2 = last ? nB : cB + (size_t)(t + 2) * kstep;
;             const char* a3 = a2 + kstep; const char* b3 = b2 + kstep;
;             PG8_LDB(B0, 0, 0); PG8_SCHED; PG8_LDA(At, 0, 0); PG8_STAGE(PG8_SA(1, 1), a1 + hstep, voffA);
;             PG8_WAIT_L(8); PG8_BAR; PG8_WAIT_L(0); PG8_MMA(0, 0, At, B0); PG8_BAR; PG8_SCHED;
.LBB0_145:
	s_add_i32 s6, 0, 0x10000
	ds_read_b128 v[136:139], v244
	ds_read_b128 v[140:143], v244 offset:1024
	ds_read_b128 v[144:147], v244 offset:2048
	ds_read_b128 v[148:151], v244 offset:3072
	v_cmp_eq_u32_e32 vcc, s4, v135
	s_add_i32 s5, s4, 2
	s_add_i32 m0, s2, 0xc000
	ds_read_b128 v[152:155], v233
	ds_read_b128 v[156:159], v233 offset:1024
	ds_read_b128 v[160:163], v233 offset:2048
	ds_read_b128 v[184:187], v233 offset:3072
	ds_read_b128 v[188:191], v233 offset:4096
	ds_read_b128 v[192:195], v233 offset:5120
	ds_read_b128 v[196:199], v233 offset:6144
	ds_read_b128 v[200:203], v233 offset:7168
	global_load_lds_dwordx4 v174, s[98:99]
	s_add_i32 m0, s2, 0xe000
	s_nop 0
	global_load_lds_dwordx4 v176, s[98:99]
	s_waitcnt lgkmcnt(8)
	s_barrier
	s_waitcnt lgkmcnt(0)
	v_mfma_f32_16x16x32_bf16 v[126:129], v[136:139], v[152:155], v[126:129]
	v_mfma_f32_16x16x32_bf16 v[122:125], v[144:147], v[152:155], v[122:125]
	v_mfma_f32_16x16x32_bf16 v[110:113], v[136:139], v[160:163], v[110:113]
	v_mfma_f32_16x16x32_bf16 v[106:109], v[144:147], v[160:163], v[106:109]
	v_mfma_f32_16x16x32_bf16 v[94:97], v[136:139], v[188:191], v[94:97]
	v_mfma_f32_16x16x32_bf16 v[90:93], v[144:147], v[188:191], v[90:93]
	v_mfma_f32_16x16x32_bf16 v[78:81], v[136:139], v[196:199], v[78:81]
	v_mfma_f32_16x16x32_bf16 v[74:77], v[144:147], v[196:199], v[74:77]
	v_mfma_f32_16x16x32_bf16 v[126:129], v[140:143], v[156:159], v[126:129]
	v_mfma_f32_16x16x32_bf16 v[122:125], v[148:151], v[156:159], v[122:125]
	v_mfma_f32_16x16x32_bf16 v[110:113], v[140:143], v[184:187], v[110:113]
	v_mfma_f32_16x16x32_bf16 v[106:109], v[148:151], v[184:187], v[106:109]
	v_mfma_f32_16x16x32_bf16 v[94:97], v[140:143], v[192:195], v[94:97]
	v_mfma_f32_16x16x32_bf16 v[90:93], v[148:151], v[192:195], v[90:93]
	v_mfma_f32_16x16x32_bf16 v[78:81], v[140:143], v[200:203], v[78:81]
	v_mfma_f32_16x16x32_bf16 v[74:77], v[148:151], v[200:203], v[74:77]
	s_barrier
	s_cbranch_vccz .Lkl_notlast
	v_readfirstlane_b32 s98, v180
	v_readfirstlane_b32 s99, v181
	v_readfirstlane_b32 s100, v182
	v_readfirstlane_b32 s101, v183
	s_branch .Lkl_ptr_done

; #define PG8_STAGE(bufoff, gbase, voff) do { _Pragma("unroll") for (int _i = 0; _i < 2; ++_i) \
;         __builtin_amdgcn_global_load_lds((const unsigned*)((const char*)(gbase) + (voff)[_i]), (LAS unsigned*)(lds + (bufoff) + ldsw + _i * 8192), 16, 0, 0); } while (0)
; #define PG8_LDA(dst, b, h) do { _Pragma("unroll") for (int m = 0; m < 4; ++m) _Pragma("unroll") for (int k = 0; k < 2; ++k) dst[m][k] = *(const LAS bf16x8*)(lds + PG8_SA(b, h) + aoff + m * 2048 + k * 1024); } while (0)
; #define PG8_LDB(dst, b, h) do { _Pragma("unroll") for (int n = 0; n < 2; ++n) _Pragma("unroll") for (int k = 0; k < 2; ++k) dst[n][k] = *(const LAS bf16x8*)(lds + PG8_SB(b, h) + boff + n * 2048 + k * 1024); } while (0)
; #define PG8_MMA(ai, bj, At, Bt) do { __builtin_amdgcn_s_setprio(1); _Pragma("unroll") for (int m = 0; m < 4; ++m) _Pragma("unroll") for (int n = 0; n < 2; ++n) _Pragma("unroll") for (int k = 0; k < 2; ++k) \
;         acc[ai][bj][m][n] = __builtin_amdgcn_mfma_f32_16x16x32_bf16(Bt[n][k], At[m][k], acc[ai][bj][m][n], 0, 0, 0); __builtin_amdgcn_s_setprio(0); } while (0)
; #define PG8_WAIT_V(n) asm volatile("s_waitcnt vmcnt(" #n ")" ::: "memory")
; #define PG8_WAIT_L(n) asm volatile("s_waitcnt lgkmcnt(" #n ")" ::: "memory")
; #define PG8_BAR __builtin_amdgcn_s_barrier()
; #define PG8_SCHED __builtin_amdgcn_sched_barrier(0)
; __device__ __forceinline__ void gemm_phase(LAS unsigned char* lds, const GemmD& g) {
;     ...
;             PG8_LDB(B1, 0, 1); PG8_STAGE(PG8_SB(0, 0), b2, voffB);
;             PG8_BAR; PG8_WAIT_L(0); PG8_MMA(0, 1, At, B1); PG8_BAR;
;             PG8_LDA(At, 0, 1); PG8_STAGE(PG8_SA(0, 0), a2, voffA);
;             PG8_BAR; PG8_WAIT_L(0); PG8_MMA(1, 0, At, B0); PG8_BAR; PG8_SCHED;
;             PG8_STAGE(PG8_SB(0, 1), b2 + hstep, voffB);
;             PG8_WAIT_V(6); PG8_BAR; PG8_MMA(1, 1, At, B1); PG8_BAR;
;             PG8_LDB(B0, 1, 0); PG8_SCHED; PG8_LDA(At, 1, 0); PG8_STAGE(PG8_SA(0, 1), a2 + hstep, voffA);
.Lkl_ptr_done:
	s_add_i32 s4, 0, 0x14000
	s_add_i32 s6, s6, s87
	s_mov_b32 m0, s6
	ds_read_b128 v[204:207], v245
	ds_read_b128 v[208:211], v245 offset:1024
	ds_read_b128 v[234:237], v245 offset:2048
	ds_read_b128 v[238:241], v245 offset:3072
	global_load_lds_dwordx4 v172, s[100:101]
	s_add_i32 m0, s6, 0x2000
	s_nop 0
	global_load_lds_dwordx4 v168, s[100:101]
	s_barrier
	s_waitcnt lgkmcnt(0)
	v_mfma_f32_16x16x32_bf16 v[118:121], v[204:207], v[152:155], v[118:121]
	v_mfma_f32_16x16x32_bf16 v[114:117], v[234:237], v[152:155], v[114:117]
	v_mfma_f32_16x16x32_bf16 v[102:105], v[204:207], v[160:163], v[102:105]
	v_mfma_f32_16x16x32_bf16 v[98:101], v[234:237], v[160:163], v[98:101]
	v_mfma_f32_16x16x32_bf16 v[86:89], v[204:207], v[188:191], v[86:89]
	v_mfma_f32_16x16x32_bf16 v[82:85], v[234:237], v[188:191], v[82:85]
	v_mfma_f32_16x16x32_bf16 v[70:73], v[204:207], v[196:199], v[70:73]
	v_mfma_f32_16x16x32_bf16 v[66:69], v[234:237], v[196:199], v[66:69]
	v_mfma_f32_16x16x32_bf16 v[118:121], v[208:211], v[156:159], v[118:121]
	v_mfma_f32_16x16x32_bf16 v[114:117], v[238:241], v[156:159], v[114:117]
	v_mfma_f32_16x16x32_bf16 v[102:105], v[208:211], v[184:187], v[102:105]
	v_mfma_f32_16x16x32_bf16 v[98:101], v[238:241], v[184:187], v[98:101]
	v_mfma_f32_16x16x32_bf16 v[86:89], v[208:211], v[192:195], v[86:89]
	v_mfma_f32_16x16x32_bf16 v[82:85], v[238:241], v[192:195], v[82:85]
	v_mfma_f32_16x16x32_bf16 v[70:73], v[208:211], v[200:203], v[70:73]
	v_mfma_f32_16x16x32_bf16 v[66:69], v[238:241], v[200:203], v[66:69]
	s_barrier
	s_mov_b32 m0, s2
	ds_read_b128 v[152:155], v233 offset:16384
	ds_read_b128 v[156:159], v233 offset:17408
	ds_read_b128 v[160:163], v233 offset:18432
	ds_read_b128 v[184:187], v233 offset:19456
	ds_read_b128 v[188:191], v233 offset:20480
	ds_read_b128 v[192:195], v233 offset:21504
	ds_read_b128 v[196:199], v233 offset:22528
	ds_read_b128 v[200:203], v233 offset:23552
	global_load_lds_dwordx4 v170, s[98:99]
	s_mov_b32 m0, s3
	s_nop 0
	global_load_lds_dwordx4 v166, s[98:99]
	s_barrier
	s_waitcnt lgkmcnt(0)
	v_mfma_f32_16x16x32_bf16 v[62:65], v[136:139], v[152:155], v[62:65]
	v_mfma_f32_16x16x32_bf16 v[58:61], v[144:147], v[152:155], v[58:61]
	v_mfma_f32_16x16x32_bf16 v[46:49], v[136:139], v[160:163], v[46:49]
	v_mfma_f32_16x16x32_bf16 v[42:45], v[144:147], v[160:163], v[42:45]
	v_mfma_f32_16x16x32_bf16 v[30:33], v[136:139], v[188:191], v[30:33]
	v_mfma_f32_16x16x32_bf16 v[26:29], v[144:147], v[188:191], v[26:29]
	v_mfma_f32_16x16x32_bf16 v[14:17], v[136:139], v[196:199], v[14:17]
	v_mfma_f32_16x16x32_bf16 v[10:13], v[144:147], v[196:199], v[10:13]
	v_mfma_f32_16x16x32_bf16 v[62:65], v[140:143], v[156:159], v[62:65]
	v_mfma_f32_16x16x32_bf16 v[58:61], v[148:151], v[156:159], v[58:61]
	v_mfma_f32_16x16x32_bf16 v[46:49], v[140:143], v[184:187], v[46:49]
	v_mfma_f32_16x16x32_bf16 v[42:45], v[148:151], v[184:187], v[42:45]
	v_mfma_f32_16x16x32_bf16 v[30:33], v[140:143], v[192:195], v[30:33]
	v_mfma_f32_16x16x32_bf16 v[26:29], v[148:151], v[192:195], v[26:29]
	v_mfma_f32_16x16x32_bf16 v[14:17], v[140:143], v[200:203], v[14:17]
	v_mfma_f32_16x16x32_bf16 v[10:13], v[148:151], v[200:203], v[10:13]
	s_barrier
	s_add_i32 s4, s4, s87
	s_mov_b32 m0, s4
	s_nop 0
	global_load_lds_dwordx4 v242, s[100:101]
	s_add_i32 m0, s4, 0x2000
	s_nop 0
	global_load_lds_dwordx4 v243, s[100:101]
	s_waitcnt vmcnt(6)
	s_barrier
	v_mfma_f32_16x16x32_bf16 v[54:57], v[204:207], v[152:155], v[54:57]
	v_mfma_f32_16x16x32_bf16 v[50:53], v[234:237], v[152:155], v[50:53]
	v_mfma_f32_16x16x32_bf16 v[38:41], v[204:207], v[160:163], v[38:41]
	v_mfma_f32_16x16x32_bf16 v[34:37], v[234:237], v[160:163], v[34:37]
	v_mfma_f32_16x16x32_bf16 v[22:25], v[204:207], v[188:191], v[22:25]
	v_mfma_f32_16x16x32_bf16 v[18:21], v[234:237], v[188:191], v[18:21]
	v_mfma_f32_16x16x32_bf16 v[6:9], v[204:207], v[196:199], v[6:9]
	v_mfma_f32_16x16x32_bf16 v[2:5], v[234:237], v[196:199], v[2:5]
	v_mfma_f32_16x16x32_bf16 v[54:57], v[208:211], v[156:159], v[54:57]
	v_mfma_f32_16x16x32_bf16 v[50:53], v[238:241], v[156:159], v[50:53]
	v_mfma_f32_16x16x32_bf16 v[38:41], v[208:211], v[184:187], v[38:41]
	v_mfma_f32_16x16x32_bf16 v[34:37], v[238:241], v[184:187], v[34:37]
	v_mfma_f32_16x16x32_bf16 v[22:25], v[208:211], v[192:195], v[22:25]
	v_mfma_f32_16x16x32_bf16 v[18:21], v[238:241], v[192:195], v[18:21]
	v_mfma_f32_16x16x32_bf16 v[6:9], v[208:211], v[200:203], v[6:9]
	v_mfma_f32_16x16x32_bf16 v[2:5], v[238:241], v[200:203], v[2:5]
	s_barrier
	s_add_i32 s4, 0, 0x18000
	ds_read_b128 v[136:139], v246
	ds_read_b128 v[140:143], v246 offset:1024
	ds_read_b128 v[144:147], v246 offset:2048
	ds_read_b128 v[148:151], v246 offset:3072
	s_mov_b32 m0, s64
	ds_read_b128 v[152:155], v233 offset:32768
	ds_read_b128 v[156:159], v233 offset:33792
	ds_read_b128 v[160:163], v233 offset:34816
	ds_read_b128 v[184:187], v233 offset:35840
	ds_read_b128 v[188:191], v233 offset:36864
	ds_read_b128 v[192:195], v233 offset:37888
	ds_read_b128 v[196:199], v233 offset:38912
	ds_read_b128 v[200:203], v233 offset:39936
	global_load_lds_dwordx4 v174, s[98:99]
	s_mov_b32 m0, s65
	s_nop 0
	global_load_lds_dwordx4 v176, s[98:99]
	s_waitcnt lgkmcnt(8)
	s_barrier
; #define PG8_STAGE(bufoff, gbase, voff) do { _Pragma("unroll") for (int _i = 0; _i < 2; ++_i) \
;         __builtin_amdgcn_global_load_lds((const unsigned*)((const char*)(gbase) + (voff)[_i]), (LAS unsigned*)(lds + (bufoff) + ldsw + _i * 8192), 16, 0, 0); } while (0)
; #define PG8_LDA(dst, b, h) do { _Pragma("unroll") for (int m = 0; m < 4; ++m) _Pragma("unroll") for (int k = 0; k < 2; ++k) dst[m][k] = *(const LAS bf16x8*)(lds + PG8_SA(b, h) + aoff + m * 2048 + k * 1024); } while (0)
; #define PG8_LDB(dst, b, h) do { _Pragma("unroll") for (int n = 0; n < 2; ++n) _Pragma("unroll") for (int k = 0; k < 2; ++k) dst[n][k] = *(const LAS bf16x8*)(lds + PG8_SB(b, h) + boff + n * 2048 + k * 1024); } while (0)
; #define PG8_MMA(ai, bj, At, Bt) do { __builtin_amdgcn_s_setprio(1); _Pragma("unroll") for (int m = 0; m < 4; ++m) _Pragma("unroll") for (int n = 0; n < 2; ++n) _Pragma("unroll") for (int k = 0; k < 2; ++k) \
;         acc[ai][bj][m][n] = __builtin_amdgcn_mfma_f32_16x16x32_bf16(Bt[n][k], At[m][k], acc[ai][bj][m][n], 0, 0, 0); __builtin_amdgcn_s_setprio(0); } while (0)
; #define PG8_WAIT_V(n) asm volatile("s_waitcnt vmcnt(" #n ")" ::: "memory")
; #define PG8_WAIT_L(n) asm volatile("s_waitcnt lgkmcnt(" #n ")" ::: "memory")
; #define PG8_BAR __builtin_amdgcn_s_barrier()
; #define PG8_SCHED __builtin_amdgcn_sched_barrier(0)
; __device__ __forceinline__ void gemm_epilogue(const GemmD& g, const f32x4 (&acc)[2][2][4][2], const Unit& u, int wr, int wc, int fr, int fq) {
;     const int row0 = u.pm * BM + wr * 64 + fr;
;     const int mode = g.mode;
;     if (u.part >= 0) {
; __device__ __forceinline__ void gemm_phase(LAS unsigned char* lds, const GemmD& g) {
;     ...
;             PG8_WAIT_L(8); PG8_BAR; PG8_WAIT_L(0); PG8_MMA(0, 0, At, B0); PG8_BAR; PG8_SCHED;
;             PG8_LDB(B1, 1, 1); PG8_STAGE(PG8_SB(1, 0), b3, voffB);
;             PG8_BAR; PG8_WAIT_L(0); PG8_MMA(0, 1, At, B1); PG8_BAR;
;             PG8_LDA(At, 1, 1); PG8_STAGE(PG8_SA(1, 0), a3, voffA);
;             PG8_BAR; PG8_WAIT_L(0); PG8_MMA(1, 0, At, B0); PG8_BAR; PG8_SCHED;
;             PG8_STAGE(PG8_SB(1, 1), b3 + hstep, voffB);
;             PG8_WAIT_V(6); PG8_BAR; PG8_MMA(1, 1, At, B1); PG8_BAR;
;         }
	s_waitcnt lgkmcnt(0)
	v_mfma_f32_16x16x32_bf16 v[126:129], v[136:139], v[152:155], v[126:129]
	v_mfma_f32_16x16x32_bf16 v[122:125], v[144:147], v[152:155], v[122:125]
	v_mfma_f32_16x16x32_bf16 v[110:113], v[136:139], v[160:163], v[110:113]
	v_mfma_f32_16x16x32_bf16 v[106:109], v[144:147], v[160:163], v[106:109]
	v_mfma_f32_16x16x32_bf16 v[94:97], v[136:139], v[188:191], v[94:97]
	v_mfma_f32_16x16x32_bf16 v[90:93], v[144:147], v[188:191], v[90:93]
	v_mfma_f32_16x16x32_bf16 v[78:81], v[136:139], v[196:199], v[78:81]
	v_mfma_f32_16x16x32_bf16 v[74:77], v[144:147], v[196:199], v[74:77]
	v_mfma_f32_16x16x32_bf16 v[126:129], v[140:143], v[156:159], v[126:129]
	v_mfma_f32_16x16x32_bf16 v[122:125], v[148:151], v[156:159], v[122:125]
	v_mfma_f32_16x16x32_bf16 v[110:113], v[140:143], v[184:187], v[110:113]
	v_mfma_f32_16x16x32_bf16 v[106:109], v[148:151], v[184:187], v[106:109]
	v_mfma_f32_16x16x32_bf16 v[94:97], v[140:143], v[192:195], v[94:97]
	v_mfma_f32_16x16x32_bf16 v[90:93], v[148:151], v[192:195], v[90:93]
	v_mfma_f32_16x16x32_bf16 v[78:81], v[140:143], v[200:203], v[78:81]
	v_mfma_f32_16x16x32_bf16 v[74:77], v[148:151], v[200:203], v[74:77]
	s_barrier
	s_add_i32 s6, 0, 0x1c000
	s_add_i32 s4, s4, s87
	ds_read_b128 v[204:207], v247
	ds_read_b128 v[208:211], v247 offset:1024
	ds_read_b128 v[234:237], v247 offset:2048
	ds_read_b128 v[238:241], v247 offset:3072
	s_add_u32 s100, s100, 0x80
	s_addc_u32 s101, s101, 0
	s_mov_b32 m0, s4
	s_nop 0
	global_load_lds_dwordx4 v172, s[100:101]
	s_add_i32 m0, s4, 0x2000
	s_nop 0
	global_load_lds_dwordx4 v168, s[100:101]
	s_barrier
	s_waitcnt lgkmcnt(0)
	v_mfma_f32_16x16x32_bf16 v[118:121], v[204:207], v[152:155], v[118:121]
	v_mfma_f32_16x16x32_bf16 v[114:117], v[234:237], v[152:155], v[114:117]
	v_mfma_f32_16x16x32_bf16 v[102:105], v[204:207], v[160:163], v[102:105]
	v_mfma_f32_16x16x32_bf16 v[98:101], v[234:237], v[160:163], v[98:101]
	v_mfma_f32_16x16x32_bf16 v[86:89], v[204:207], v[188:191], v[86:89]
	v_mfma_f32_16x16x32_bf16 v[82:85], v[234:237], v[188:191], v[82:85]
	v_mfma_f32_16x16x32_bf16 v[70:73], v[204:207], v[196:199], v[70:73]
	v_mfma_f32_16x16x32_bf16 v[66:69], v[234:237], v[196:199], v[66:69]
	v_mfma_f32_16x16x32_bf16 v[118:121], v[208:211], v[156:159], v[118:121]
	v_mfma_f32_16x16x32_bf16 v[114:117], v[238:241], v[156:159], v[114:117]
	v_mfma_f32_16x16x32_bf16 v[102:105], v[208:211], v[184:187], v[102:105]
	v_mfma_f32_16x16x32_bf16 v[98:101], v[238:241], v[184:187], v[98:101]
	v_mfma_f32_16x16x32_bf16 v[86:89], v[208:211], v[192:195], v[86:89]
	v_mfma_f32_16x16x32_bf16 v[82:85], v[238:241], v[192:195], v[82:85]
	v_mfma_f32_16x16x32_bf16 v[70:73], v[208:211], v[200:203], v[70:73]
	v_mfma_f32_16x16x32_bf16 v[66:69], v[238:241], v[200:203], v[66:69]
	s_barrier
	s_mov_b32 m0, s28
	s_add_u32 s98, s98, 0x80
	s_addc_u32 s99, s99, 0
	ds_read_b128 v[152:155], v233 offset:49152
	ds_read_b128 v[156:159], v233 offset:50176
	ds_read_b128 v[160:163], v233 offset:51200
	ds_read_b128 v[184:187], v233 offset:52224
	ds_read_b128 v[188:191], v233 offset:53248
	ds_read_b128 v[192:195], v233 offset:54272
	ds_read_b128 v[196:199], v233 offset:55296
	ds_read_b128 v[200:203], v233 offset:56320
	global_load_lds_dwordx4 v170, s[98:99]
	s_mov_b32 m0, s29
	s_nop 0
	global_load_lds_dwordx4 v166, s[98:99]
	s_barrier
	s_waitcnt lgkmcnt(0)
	v_mfma_f32_16x16x32_bf16 v[62:65], v[136:139], v[152:155], v[62:65]
	v_mfma_f32_16x16x32_bf16 v[58:61], v[144:147], v[152:155], v[58:61]
	v_mfma_f32_16x16x32_bf16 v[46:49], v[136:139], v[160:163], v[46:49]
	v_mfma_f32_16x16x32_bf16 v[42:45], v[144:147], v[160:163], v[42:45]
	v_mfma_f32_16x16x32_bf16 v[30:33], v[136:139], v[188:191], v[30:33]
	v_mfma_f32_16x16x32_bf16 v[26:29], v[144:147], v[188:191], v[26:29]
	v_mfma_f32_16x16x32_bf16 v[14:17], v[136:139], v[196:199], v[14:17]
	v_mfma_f32_16x16x32_bf16 v[10:13], v[144:147], v[196:199], v[10:13]
	v_mfma_f32_16x16x32_bf16 v[62:65], v[140:143], v[156:159], v[62:65]
	v_mfma_f32_16x16x32_bf16 v[58:61], v[148:151], v[156:159], v[58:61]
	v_mfma_f32_16x16x32_bf16 v[46:49], v[140:143], v[184:187], v[46:49]
	v_mfma_f32_16x16x32_bf16 v[42:45], v[148:151], v[184:187], v[42:45]
	v_mfma_f32_16x16x32_bf16 v[30:33], v[140:143], v[192:195], v[30:33]
	v_mfma_f32_16x16x32_bf16 v[26:29], v[148:151], v[192:195], v[26:29]
	v_mfma_f32_16x16x32_bf16 v[14:17], v[140:143], v[200:203], v[14:17]
	v_mfma_f32_16x16x32_bf16 v[10:13], v[148:151], v[200:203], v[10:13]
	s_barrier
	s_add_i32 s4, s6, s87
	s_mov_b32 m0, s4
	s_nop 0
	global_load_lds_dwordx4 v242, s[100:101]
	s_add_i32 m0, s4, 0x2000
	s_nop 0
	global_load_lds_dwordx4 v243, s[100:101]
	s_add_u32 s100, s100, 0x80
	s_addc_u32 s101, s101, 0
	s_mov_b32 s4, s5
	s_waitcnt vmcnt(6)
	s_barrier
	v_mfma_f32_16x16x32_bf16 v[54:57], v[204:207], v[152:155], v[54:57]
	v_mfma_f32_16x16x32_bf16 v[50:53], v[234:237], v[152:155], v[50:53]
	v_mfma_f32_16x16x32_bf16 v[38:41], v[204:207], v[160:163], v[38:41]
	v_mfma_f32_16x16x32_bf16 v[34:37], v[234:237], v[160:163], v[34:37]
	v_mfma_f32_16x16x32_bf16 v[22:25], v[204:207], v[188:191], v[22:25]
	v_mfma_f32_16x16x32_bf16 v[18:21], v[234:237], v[188:191], v[18:21]
	v_mfma_f32_16x16x32_bf16 v[6:9], v[204:207], v[196:199], v[6:9]
	v_mfma_f32_16x16x32_bf16 v[2:5], v[234:237], v[196:199], v[2:5]
	v_mfma_f32_16x16x32_bf16 v[54:57], v[208:211], v[156:159], v[54:57]
	v_mfma_f32_16x16x32_bf16 v[50:53], v[238:241], v[156:159], v[50:53]
	v_mfma_f32_16x16x32_bf16 v[38:41], v[208:211], v[184:187], v[38:41]
	v_mfma_f32_16x16x32_bf16 v[34:37], v[238:241], v[184:187], v[34:37]
	v_mfma_f32_16x16x32_bf16 v[22:25], v[208:211], v[192:195], v[22:25]
	v_mfma_f32_16x16x32_bf16 v[18:21], v[238:241], v[192:195], v[18:21]
	v_mfma_f32_16x16x32_bf16 v[6:9], v[208:211], v[200:203], v[6:9]
	v_mfma_f32_16x16x32_bf16 v[2:5], v[238:241], v[200:203], v[2:5]
	s_barrier
	s_cbranch_vccz .LBB0_145
	v_lshl_add_u32 v184, s56, 8, v228
	s_cmp_lt_i32 s66, 0
	s_mov_b64 s[4:5], -1
	s_cbranch_scc0 .LBB0_704
